# v29: GU epilogue blocks 2-7 process all four column pairs interleaved (4 temp pairs), block 1 two at a time; row scales packed two per register pair
# baseline (speedup 1.0000x reference)
; #define PG8_LAS __attribute__((address_space(3)))
; __device__ __forceinline__ u32x4 pack8(const f32x4 a, const f32x4 b) { u32x4 w; w.x = cvt_pk_bf16(a[0], a[1]); w.y = cvt_pk_bf16(a[2], a[3]); w.z = cvt_pk_bf16(b[0], b[1]); w.w = cvt_pk_bf16(b[2], b[3]); return w; }
;     __device__ __forceinline__ void operator()(const f32x4 (&acc)[2][2][4][2], const Unit& u, int wr, int wc, int fr, int fq) const {
;         PG8_LAS const float* R = stage_rstd((const float*)(ws + WS_PS), lds, u.pm);
; #pragma unroll
;         for (int ai = 0; ai < 2; ++ai)
; #pragma unroll
;             for (int m = 0; m < 4; ++m) {
;                 const int row = u.pm * BM + ai * HALF + wr * 64 + m * 16 + fr;
;                 const float rs = R[ai * HALF + wr * 64 + m * 16 + fr];
;                 bf16_t* ACT = (bf16_t*)(ws + WS_ACT);
;                 f32x4 a[2];
; #pragma unroll
;                 for (int n = 0; n < 2; ++n) {
;                     const f32x4 g = acc[ai][0][m][n] * rs, uu = acc[ai][1][m][n] * rs;
; #pragma unroll
;                     for (int j = 0; j < 4; ++j) a[n][j] = g[j] * __builtin_amdgcn_rcpf(1.0f + __builtin_amdgcn_exp2f(-1.4426950408889634f * g[j])) * uu[j];
;                 }
;                 *(u32x4*)(ACT + (size_t)row * 2816 + u.pn * 128 + wc * 32 + 8 * fq) = pack8(a[0], a[1]);
;             }
.LBB0_38:
	s_lshl_b32 s3, s48, 8
	ds_read_b32 v146, v142
	v_mov_b32_e32 v145, 0xbfb8aa3b
	s_waitcnt lgkmcnt(0)
	v_pk_mul_f32 v[124:125], v[124:125], v[146:147] op_sel_hi:[1,0]
	v_pk_mul_f32 v[126:127], v[126:127], v[146:147] op_sel_hi:[1,0]
	v_pk_mul_f32 v[116:117], v[116:117], v[146:147] op_sel_hi:[1,0]
	v_pk_mul_f32 v[118:119], v[118:119], v[146:147] op_sel_hi:[1,0]
	v_pk_mul_f32 v[120:121], v[120:121], v[146:147] op_sel_hi:[1,0]
	v_pk_mul_f32 v[122:123], v[122:123], v[146:147] op_sel_hi:[1,0]
	v_pk_mul_f32 v[112:113], v[112:113], v[146:147] op_sel_hi:[1,0]
	v_pk_mul_f32 v[114:115], v[114:115], v[146:147] op_sel_hi:[1,0]
	v_pk_mul_f32 v[148:149], v[124:125], v[144:145] op_sel:[0,1] op_sel_hi:[1,1]
	v_exp_f32_e32 v148, v148
	v_exp_f32_e32 v149, v149
	v_add_f32_e32 v148, 1.0, v148
	v_add_f32_e32 v149, 1.0, v149
	v_rcp_f32_e32 v148, v148
	v_rcp_f32_e32 v149, v149
	s_nop 0
	v_pk_mul_f32 v[124:125], v[124:125], v[148:149]
	v_pk_mul_f32 v[120:121], v[120:121], v[124:125]
	v_pk_mul_f32 v[148:149], v[126:127], v[144:145] op_sel:[0,1] op_sel_hi:[1,1]
	v_exp_f32_e32 v148, v148
	v_exp_f32_e32 v149, v149
	v_add_f32_e32 v148, 1.0, v148
	v_add_f32_e32 v149, 1.0, v149
	v_rcp_f32_e32 v148, v148
	v_rcp_f32_e32 v149, v149
	s_nop 0
	v_pk_mul_f32 v[126:127], v[126:127], v[148:149]
	v_pk_mul_f32 v[122:123], v[122:123], v[126:127]
	v_pk_mul_f32 v[148:149], v[116:117], v[144:145] op_sel:[0,1] op_sel_hi:[1,1]
	v_exp_f32_e32 v148, v148
	v_exp_f32_e32 v149, v149
	v_add_f32_e32 v148, 1.0, v148
	v_add_f32_e32 v149, 1.0, v149
	v_rcp_f32_e32 v148, v148
	v_rcp_f32_e32 v149, v149
	s_nop 0
	v_pk_mul_f32 v[116:117], v[116:117], v[148:149]
	v_pk_mul_f32 v[112:113], v[112:113], v[116:117]
	v_pk_mul_f32 v[148:149], v[118:119], v[144:145] op_sel:[0,1] op_sel_hi:[1,1]
	v_exp_f32_e32 v148, v148
	v_exp_f32_e32 v149, v149
	v_add_f32_e32 v148, 1.0, v148
	v_add_f32_e32 v149, 1.0, v149
	v_rcp_f32_e32 v148, v148
	v_rcp_f32_e32 v149, v149
	s_nop 0
	v_pk_mul_f32 v[118:119], v[118:119], v[148:149]
	v_pk_mul_f32 v[114:115], v[114:115], v[118:119]
	v_cvt_pk_bf16_f32 v116, v112, v113
	v_cvt_pk_bf16_f32 v117, v114, v115
	v_cvt_pk_bf16_f32 v114, v120, v121
	v_cvt_pk_bf16_f32 v115, v122, v123
	s_lshl_b32 s0, s47, 7
	v_add_u32_e32 v144, s3, v140
	s_ashr_i32 s1, s0, 31
	s_movk_i32 s3, 0x1600
	s_lshl_b64 s[0:1], s[0:1], 1
	s_andn2_b64 vcc, exec, s[36:37]
	v_mov_b64_e32 v[112:113], s[16:17]
	s_mov_b32 s101, 0
	v_mad_i64_i32 v[118:119], s[4:5], v144, s3, v[112:113]
	v_lshl_add_u64 v[118:119], v[118:119], 0, s[0:1]
	v_lshl_add_u64 v[118:119], v[118:119], 0, s[34:35]
	v_lshl_add_u64 v[118:119], v[118:119], 0, v[184:185]
	global_store_dwordx4 v[118:119], v[114:117], off
	ds_read_b32 v114, v142 offset:64
	ds_read_b32 v120, v142 offset:128
	ds_read_b32 v121, v142 offset:192
	ds_read_b32 v122, v142 offset:512
	ds_read_b32 v123, v142 offset:576
	ds_read_b32 v124, v142 offset:640
	ds_read_b32 v125, v142 offset:704
	v_mov_b32_e32 v116, 1.0
	s_waitcnt lgkmcnt(6)
	v_pk_mul_f32 v[108:109], v[108:109], v[114:115] op_sel_hi:[1,0]
	v_pk_mul_f32 v[110:111], v[110:111], v[114:115] op_sel_hi:[1,0]
	v_pk_mul_f32 v[100:101], v[100:101], v[114:115] op_sel_hi:[1,0]
	v_pk_mul_f32 v[102:103], v[102:103], v[114:115] op_sel_hi:[1,0]
	v_pk_mul_f32 v[104:105], v[104:105], v[114:115] op_sel_hi:[1,0]
	v_pk_mul_f32 v[106:107], v[106:107], v[114:115] op_sel_hi:[1,0]
	v_pk_mul_f32 v[96:97], v[96:97], v[114:115] op_sel_hi:[1,0]
	v_pk_mul_f32 v[98:99], v[98:99], v[114:115] op_sel_hi:[1,0]
	v_pk_mul_f32 v[148:149], v[108:109], v[144:145] op_sel:[0,1] op_sel_hi:[1,1]
	v_pk_mul_f32 v[126:127], v[110:111], v[144:145] op_sel:[0,1] op_sel_hi:[1,1]
	v_exp_f32_e32 v148, v148
	v_exp_f32_e32 v149, v149
	v_exp_f32_e32 v126, v126
	v_exp_f32_e32 v127, v127
	v_pk_add_f32 v[148:149], v[148:149], v[116:117] op_sel_hi:[1,0]
	v_pk_add_f32 v[126:127], v[126:127], v[116:117] op_sel_hi:[1,0]
	v_rcp_f32_e32 v148, v148
	v_rcp_f32_e32 v149, v149
	v_rcp_f32_e32 v126, v126
	v_rcp_f32_e32 v127, v127
	v_pk_mul_f32 v[108:109], v[108:109], v[148:149]
	v_pk_mul_f32 v[110:111], v[110:111], v[126:127]
	v_pk_mul_f32 v[104:105], v[104:105], v[108:109]
	v_pk_mul_f32 v[106:107], v[106:107], v[110:111]
	v_pk_mul_f32 v[148:149], v[100:101], v[144:145] op_sel:[0,1] op_sel_hi:[1,1]
	v_pk_mul_f32 v[126:127], v[102:103], v[144:145] op_sel:[0,1] op_sel_hi:[1,1]
	v_exp_f32_e32 v148, v148
	v_exp_f32_e32 v149, v149
	v_exp_f32_e32 v126, v126
	v_exp_f32_e32 v127, v127
	v_pk_add_f32 v[148:149], v[148:149], v[116:117] op_sel_hi:[1,0]
	v_pk_add_f32 v[126:127], v[126:127], v[116:117] op_sel_hi:[1,0]
	v_rcp_f32_e32 v148, v148
	v_rcp_f32_e32 v149, v149
	v_rcp_f32_e32 v126, v126
	v_rcp_f32_e32 v127, v127
	v_pk_mul_f32 v[100:101], v[100:101], v[148:149]
	v_pk_mul_f32 v[102:103], v[102:103], v[126:127]
	v_pk_mul_f32 v[96:97], v[96:97], v[100:101]
	v_pk_mul_f32 v[98:99], v[98:99], v[102:103]
	v_cvt_pk_bf16_f32 v99, v98, v99
	v_cvt_pk_bf16_f32 v98, v96, v97
	v_cvt_pk_bf16_f32 v96, v104, v105
	v_cvt_pk_bf16_f32 v97, v106, v107
	s_mov_b32 s100, 0x16000
	v_lshl_add_u64 v[100:101], v[118:119], 0, s[100:101]
	global_store_dwordx4 v[100:101], v[96:99], off
	s_waitcnt lgkmcnt(0)
; __device__ __forceinline__ u32x4 pack8(const f32x4 a, const f32x4 b) { u32x4 w; w.x = cvt_pk_bf16(a[0], a[1]); w.y = cvt_pk_bf16(a[2], a[3]); w.z = cvt_pk_bf16(b[0], b[1]); w.w = cvt_pk_bf16(b[2], b[3]); return w; }
;     __device__ __forceinline__ void operator()(const f32x4 (&acc)[2][2][4][2], const Unit& u, int wr, int wc, int fr, int fq) const {
;     ...
;         for (int ai = 0; ai < 2; ++ai)
; #pragma unroll
;             for (int m = 0; m < 4; ++m) {
;                 const int row = u.pm * BM + ai * HALF + wr * 64 + m * 16 + fr;
;                 const float rs = R[ai * HALF + wr * 64 + m * 16 + fr];
;                 bf16_t* ACT = (bf16_t*)(ws + WS_ACT);
;                 f32x4 a[2];
; #pragma unroll
;                 for (int n = 0; n < 2; ++n) {
;                     const f32x4 g = acc[ai][0][m][n] * rs, uu = acc[ai][1][m][n] * rs;
; #pragma unroll
;                     for (int j = 0; j < 4; ++j) a[n][j] = g[j] * __builtin_amdgcn_rcpf(1.0f + __builtin_amdgcn_exp2f(-1.4426950408889634f * g[j])) * uu[j];
;                 }
;                 *(u32x4*)(ACT + (size_t)row * 2816 + u.pn * 128 + wc * 32 + 8 * fq) = pack8(a[0], a[1]);
;             }
	v_pk_mul_f32 v[92:93], v[92:93], v[120:121] op_sel_hi:[1,0]
	v_pk_mul_f32 v[94:95], v[94:95], v[120:121] op_sel_hi:[1,0]
	v_pk_mul_f32 v[84:85], v[84:85], v[120:121] op_sel_hi:[1,0]
	v_pk_mul_f32 v[86:87], v[86:87], v[120:121] op_sel_hi:[1,0]
	v_pk_mul_f32 v[88:89], v[88:89], v[120:121] op_sel_hi:[1,0]
	v_pk_mul_f32 v[90:91], v[90:91], v[120:121] op_sel_hi:[1,0]
	v_pk_mul_f32 v[80:81], v[80:81], v[120:121] op_sel_hi:[1,0]
	v_pk_mul_f32 v[82:83], v[82:83], v[120:121] op_sel_hi:[1,0]
	v_pk_mul_f32 v[148:149], v[92:93], v[144:145] op_sel:[0,1] op_sel_hi:[1,1]
	v_pk_mul_f32 v[114:115], v[94:95], v[144:145] op_sel:[0,1] op_sel_hi:[1,1]
	v_pk_mul_f32 v[126:127], v[84:85], v[144:145] op_sel:[0,1] op_sel_hi:[1,1]
	v_pk_mul_f32 v[112:113], v[86:87], v[144:145] op_sel:[0,1] op_sel_hi:[1,1]
	v_exp_f32_e32 v148, v148
	v_exp_f32_e32 v149, v149
	v_exp_f32_e32 v114, v114
	v_exp_f32_e32 v115, v115
	v_exp_f32_e32 v126, v126
	v_exp_f32_e32 v127, v127
	v_exp_f32_e32 v112, v112
	v_exp_f32_e32 v113, v113
	v_pk_add_f32 v[148:149], v[148:149], v[116:117] op_sel_hi:[1,0]
	v_pk_add_f32 v[114:115], v[114:115], v[116:117] op_sel_hi:[1,0]
	v_pk_add_f32 v[126:127], v[126:127], v[116:117] op_sel_hi:[1,0]
	v_pk_add_f32 v[112:113], v[112:113], v[116:117] op_sel_hi:[1,0]
	v_rcp_f32_e32 v148, v148
	v_rcp_f32_e32 v149, v149
	v_rcp_f32_e32 v114, v114
	v_rcp_f32_e32 v115, v115
	v_rcp_f32_e32 v126, v126
	v_rcp_f32_e32 v127, v127
	v_rcp_f32_e32 v112, v112
	v_rcp_f32_e32 v113, v113
	v_pk_mul_f32 v[92:93], v[92:93], v[148:149]
	v_pk_mul_f32 v[94:95], v[94:95], v[114:115]
	v_pk_mul_f32 v[84:85], v[84:85], v[126:127]
	v_pk_mul_f32 v[86:87], v[86:87], v[112:113]
	v_pk_mul_f32 v[88:89], v[88:89], v[92:93]
	v_pk_mul_f32 v[90:91], v[90:91], v[94:95]
	v_pk_mul_f32 v[80:81], v[80:81], v[84:85]
	v_pk_mul_f32 v[82:83], v[82:83], v[86:87]
	v_cvt_pk_bf16_f32 v83, v82, v83
	v_cvt_pk_bf16_f32 v82, v80, v81
	v_cvt_pk_bf16_f32 v80, v88, v89
	v_cvt_pk_bf16_f32 v81, v90, v91
	s_mov_b32 s100, 0x2c000
	v_lshl_add_u64 v[84:85], v[118:119], 0, s[100:101]
	global_store_dwordx4 v[84:85], v[80:83], off
	s_waitcnt lgkmcnt(0)
	v_pk_mul_f32 v[76:77], v[76:77], v[120:121] op_sel:[0,1] op_sel_hi:[1,1]
	v_pk_mul_f32 v[78:79], v[78:79], v[120:121] op_sel:[0,1] op_sel_hi:[1,1]
	v_pk_mul_f32 v[68:69], v[68:69], v[120:121] op_sel:[0,1] op_sel_hi:[1,1]
	v_pk_mul_f32 v[70:71], v[70:71], v[120:121] op_sel:[0,1] op_sel_hi:[1,1]
	v_pk_mul_f32 v[72:73], v[72:73], v[120:121] op_sel:[0,1] op_sel_hi:[1,1]
	v_pk_mul_f32 v[74:75], v[74:75], v[120:121] op_sel:[0,1] op_sel_hi:[1,1]
	v_pk_mul_f32 v[64:65], v[64:65], v[120:121] op_sel:[0,1] op_sel_hi:[1,1]
	v_pk_mul_f32 v[66:67], v[66:67], v[120:121] op_sel:[0,1] op_sel_hi:[1,1]
	v_pk_mul_f32 v[148:149], v[76:77], v[144:145] op_sel:[0,1] op_sel_hi:[1,1]
	v_pk_mul_f32 v[114:115], v[78:79], v[144:145] op_sel:[0,1] op_sel_hi:[1,1]
	v_pk_mul_f32 v[126:127], v[68:69], v[144:145] op_sel:[0,1] op_sel_hi:[1,1]
	v_pk_mul_f32 v[112:113], v[70:71], v[144:145] op_sel:[0,1] op_sel_hi:[1,1]
	v_exp_f32_e32 v148, v148
	v_exp_f32_e32 v149, v149
	v_exp_f32_e32 v114, v114
	v_exp_f32_e32 v115, v115
	v_exp_f32_e32 v126, v126
	v_exp_f32_e32 v127, v127
	v_exp_f32_e32 v112, v112
	v_exp_f32_e32 v113, v113
	v_pk_add_f32 v[148:149], v[148:149], v[116:117] op_sel_hi:[1,0]
	v_pk_add_f32 v[114:115], v[114:115], v[116:117] op_sel_hi:[1,0]
	v_pk_add_f32 v[126:127], v[126:127], v[116:117] op_sel_hi:[1,0]
	v_pk_add_f32 v[112:113], v[112:113], v[116:117] op_sel_hi:[1,0]
	v_rcp_f32_e32 v148, v148
	v_rcp_f32_e32 v149, v149
	v_rcp_f32_e32 v114, v114
	v_rcp_f32_e32 v115, v115
	v_rcp_f32_e32 v126, v126
	v_rcp_f32_e32 v127, v127
	v_rcp_f32_e32 v112, v112
	v_rcp_f32_e32 v113, v113
	v_pk_mul_f32 v[76:77], v[76:77], v[148:149]
	v_pk_mul_f32 v[78:79], v[78:79], v[114:115]
	v_pk_mul_f32 v[68:69], v[68:69], v[126:127]
	v_pk_mul_f32 v[70:71], v[70:71], v[112:113]
	v_pk_mul_f32 v[72:73], v[72:73], v[76:77]
	v_pk_mul_f32 v[74:75], v[74:75], v[78:79]
	v_pk_mul_f32 v[64:65], v[64:65], v[68:69]
	v_pk_mul_f32 v[66:67], v[66:67], v[70:71]
	v_cvt_pk_bf16_f32 v67, v66, v67
	v_cvt_pk_bf16_f32 v66, v64, v65
	v_cvt_pk_bf16_f32 v64, v72, v73
	v_cvt_pk_bf16_f32 v65, v74, v75
	s_mov_b32 s100, 0x42000
	v_lshl_add_u64 v[68:69], v[118:119], 0, s[100:101]
	global_store_dwordx4 v[68:69], v[64:67], off
	s_waitcnt lgkmcnt(0)
	v_pk_mul_f32 v[60:61], v[60:61], v[122:123] op_sel_hi:[1,0]
	v_pk_mul_f32 v[62:63], v[62:63], v[122:123] op_sel_hi:[1,0]
	v_pk_mul_f32 v[52:53], v[52:53], v[122:123] op_sel_hi:[1,0]
	v_pk_mul_f32 v[54:55], v[54:55], v[122:123] op_sel_hi:[1,0]
	v_pk_mul_f32 v[56:57], v[56:57], v[122:123] op_sel_hi:[1,0]
	v_pk_mul_f32 v[58:59], v[58:59], v[122:123] op_sel_hi:[1,0]
	v_pk_mul_f32 v[48:49], v[48:49], v[122:123] op_sel_hi:[1,0]
	v_pk_mul_f32 v[50:51], v[50:51], v[122:123] op_sel_hi:[1,0]
	v_pk_mul_f32 v[148:149], v[60:61], v[144:145] op_sel:[0,1] op_sel_hi:[1,1]
	v_pk_mul_f32 v[114:115], v[62:63], v[144:145] op_sel:[0,1] op_sel_hi:[1,1]
	v_pk_mul_f32 v[126:127], v[52:53], v[144:145] op_sel:[0,1] op_sel_hi:[1,1]
	v_pk_mul_f32 v[112:113], v[54:55], v[144:145] op_sel:[0,1] op_sel_hi:[1,1]
	v_exp_f32_e32 v148, v148
	v_exp_f32_e32 v149, v149
	v_exp_f32_e32 v114, v114
	v_exp_f32_e32 v115, v115
	v_exp_f32_e32 v126, v126
	v_exp_f32_e32 v127, v127
	v_exp_f32_e32 v112, v112
	v_exp_f32_e32 v113, v113
	v_pk_add_f32 v[148:149], v[148:149], v[116:117] op_sel_hi:[1,0]
	v_pk_add_f32 v[114:115], v[114:115], v[116:117] op_sel_hi:[1,0]
	v_pk_add_f32 v[126:127], v[126:127], v[116:117] op_sel_hi:[1,0]
	v_pk_add_f32 v[112:113], v[112:113], v[116:117] op_sel_hi:[1,0]
	v_rcp_f32_e32 v148, v148
	v_rcp_f32_e32 v149, v149
	v_rcp_f32_e32 v114, v114
	v_rcp_f32_e32 v115, v115
	v_rcp_f32_e32 v126, v126
	v_rcp_f32_e32 v127, v127
	v_rcp_f32_e32 v112, v112
	v_rcp_f32_e32 v113, v113
	v_pk_mul_f32 v[60:61], v[60:61], v[148:149]
	v_pk_mul_f32 v[62:63], v[62:63], v[114:115]
	v_pk_mul_f32 v[52:53], v[52:53], v[126:127]
	v_pk_mul_f32 v[54:55], v[54:55], v[112:113]
	v_pk_mul_f32 v[56:57], v[56:57], v[60:61]
	v_pk_mul_f32 v[58:59], v[58:59], v[62:63]
	v_pk_mul_f32 v[48:49], v[48:49], v[52:53]
	v_pk_mul_f32 v[50:51], v[50:51], v[54:55]
	v_cvt_pk_bf16_f32 v51, v50, v51
	v_cvt_pk_bf16_f32 v50, v48, v49
	v_cvt_pk_bf16_f32 v48, v56, v57
	v_cvt_pk_bf16_f32 v49, v58, v59
	s_mov_b32 s100, 0xb0000
	v_lshl_add_u64 v[52:53], v[118:119], 0, s[100:101]
	global_store_dwordx4 v[52:53], v[48:51], off
	s_waitcnt lgkmcnt(0)
; __device__ __forceinline__ u32x4 pack8(const f32x4 a, const f32x4 b) { u32x4 w; w.x = cvt_pk_bf16(a[0], a[1]); w.y = cvt_pk_bf16(a[2], a[3]); w.z = cvt_pk_bf16(b[0], b[1]); w.w = cvt_pk_bf16(b[2], b[3]); return w; }
;     __device__ __forceinline__ void operator()(const f32x4 (&acc)[2][2][4][2], const Unit& u, int wr, int wc, int fr, int fq) const {
;     ...
;         for (int ai = 0; ai < 2; ++ai)
; #pragma unroll
;             for (int m = 0; m < 4; ++m) {
;                 const int row = u.pm * BM + ai * HALF + wr * 64 + m * 16 + fr;
;                 const float rs = R[ai * HALF + wr * 64 + m * 16 + fr];
;                 bf16_t* ACT = (bf16_t*)(ws + WS_ACT);
;                 f32x4 a[2];
; #pragma unroll
;                 for (int n = 0; n < 2; ++n) {
;                     const f32x4 g = acc[ai][0][m][n] * rs, uu = acc[ai][1][m][n] * rs;
; #pragma unroll
;                     for (int j = 0; j < 4; ++j) a[n][j] = g[j] * __builtin_amdgcn_rcpf(1.0f + __builtin_amdgcn_exp2f(-1.4426950408889634f * g[j])) * uu[j];
;                 }
;                 *(u32x4*)(ACT + (size_t)row * 2816 + u.pn * 128 + wc * 32 + 8 * fq) = pack8(a[0], a[1]);
;             }
	v_pk_mul_f32 v[44:45], v[44:45], v[122:123] op_sel:[0,1] op_sel_hi:[1,1]
	v_pk_mul_f32 v[46:47], v[46:47], v[122:123] op_sel:[0,1] op_sel_hi:[1,1]
	v_pk_mul_f32 v[36:37], v[36:37], v[122:123] op_sel:[0,1] op_sel_hi:[1,1]
	v_pk_mul_f32 v[38:39], v[38:39], v[122:123] op_sel:[0,1] op_sel_hi:[1,1]
	v_pk_mul_f32 v[40:41], v[40:41], v[122:123] op_sel:[0,1] op_sel_hi:[1,1]
	v_pk_mul_f32 v[42:43], v[42:43], v[122:123] op_sel:[0,1] op_sel_hi:[1,1]
	v_pk_mul_f32 v[32:33], v[32:33], v[122:123] op_sel:[0,1] op_sel_hi:[1,1]
	v_pk_mul_f32 v[34:35], v[34:35], v[122:123] op_sel:[0,1] op_sel_hi:[1,1]
	v_pk_mul_f32 v[148:149], v[44:45], v[144:145] op_sel:[0,1] op_sel_hi:[1,1]
	v_pk_mul_f32 v[114:115], v[46:47], v[144:145] op_sel:[0,1] op_sel_hi:[1,1]
	v_pk_mul_f32 v[126:127], v[36:37], v[144:145] op_sel:[0,1] op_sel_hi:[1,1]
	v_pk_mul_f32 v[112:113], v[38:39], v[144:145] op_sel:[0,1] op_sel_hi:[1,1]
	v_exp_f32_e32 v148, v148
	v_exp_f32_e32 v149, v149
	v_exp_f32_e32 v114, v114
	v_exp_f32_e32 v115, v115
	v_exp_f32_e32 v126, v126
	v_exp_f32_e32 v127, v127
	v_exp_f32_e32 v112, v112
	v_exp_f32_e32 v113, v113
	v_pk_add_f32 v[148:149], v[148:149], v[116:117] op_sel_hi:[1,0]
	v_pk_add_f32 v[114:115], v[114:115], v[116:117] op_sel_hi:[1,0]
	v_pk_add_f32 v[126:127], v[126:127], v[116:117] op_sel_hi:[1,0]
	v_pk_add_f32 v[112:113], v[112:113], v[116:117] op_sel_hi:[1,0]
	v_rcp_f32_e32 v148, v148
	v_rcp_f32_e32 v149, v149
	v_rcp_f32_e32 v114, v114
	v_rcp_f32_e32 v115, v115
	v_rcp_f32_e32 v126, v126
	v_rcp_f32_e32 v127, v127
	v_rcp_f32_e32 v112, v112
	v_rcp_f32_e32 v113, v113
	v_pk_mul_f32 v[44:45], v[44:45], v[148:149]
	v_pk_mul_f32 v[46:47], v[46:47], v[114:115]
	v_pk_mul_f32 v[36:37], v[36:37], v[126:127]
	v_pk_mul_f32 v[38:39], v[38:39], v[112:113]
	v_pk_mul_f32 v[40:41], v[40:41], v[44:45]
	v_pk_mul_f32 v[42:43], v[42:43], v[46:47]
	v_pk_mul_f32 v[32:33], v[32:33], v[36:37]
	v_pk_mul_f32 v[34:35], v[34:35], v[38:39]
	v_cvt_pk_bf16_f32 v35, v34, v35
	v_cvt_pk_bf16_f32 v34, v32, v33
	v_cvt_pk_bf16_f32 v32, v40, v41
	v_cvt_pk_bf16_f32 v33, v42, v43
	s_mov_b32 s100, 0xc6000
	v_lshl_add_u64 v[36:37], v[118:119], 0, s[100:101]
	global_store_dwordx4 v[36:37], v[32:35], off
	s_waitcnt lgkmcnt(0)
	v_pk_mul_f32 v[28:29], v[28:29], v[124:125] op_sel_hi:[1,0]
	v_pk_mul_f32 v[30:31], v[30:31], v[124:125] op_sel_hi:[1,0]
	v_pk_mul_f32 v[20:21], v[20:21], v[124:125] op_sel_hi:[1,0]
	v_pk_mul_f32 v[22:23], v[22:23], v[124:125] op_sel_hi:[1,0]
	v_pk_mul_f32 v[24:25], v[24:25], v[124:125] op_sel_hi:[1,0]
	v_pk_mul_f32 v[26:27], v[26:27], v[124:125] op_sel_hi:[1,0]
	v_pk_mul_f32 v[16:17], v[16:17], v[124:125] op_sel_hi:[1,0]
	v_pk_mul_f32 v[18:19], v[18:19], v[124:125] op_sel_hi:[1,0]
	v_pk_mul_f32 v[148:149], v[28:29], v[144:145] op_sel:[0,1] op_sel_hi:[1,1]
	v_pk_mul_f32 v[114:115], v[30:31], v[144:145] op_sel:[0,1] op_sel_hi:[1,1]
	v_pk_mul_f32 v[126:127], v[20:21], v[144:145] op_sel:[0,1] op_sel_hi:[1,1]
	v_pk_mul_f32 v[112:113], v[22:23], v[144:145] op_sel:[0,1] op_sel_hi:[1,1]
	v_exp_f32_e32 v148, v148
	v_exp_f32_e32 v149, v149
	v_exp_f32_e32 v114, v114
	v_exp_f32_e32 v115, v115
	v_exp_f32_e32 v126, v126
	v_exp_f32_e32 v127, v127
	v_exp_f32_e32 v112, v112
	v_exp_f32_e32 v113, v113
	v_pk_add_f32 v[148:149], v[148:149], v[116:117] op_sel_hi:[1,0]
	v_pk_add_f32 v[114:115], v[114:115], v[116:117] op_sel_hi:[1,0]
	v_pk_add_f32 v[126:127], v[126:127], v[116:117] op_sel_hi:[1,0]
	v_pk_add_f32 v[112:113], v[112:113], v[116:117] op_sel_hi:[1,0]
	v_rcp_f32_e32 v148, v148
	v_rcp_f32_e32 v149, v149
	v_rcp_f32_e32 v114, v114
	v_rcp_f32_e32 v115, v115
	v_rcp_f32_e32 v126, v126
	v_rcp_f32_e32 v127, v127
	v_rcp_f32_e32 v112, v112
	v_rcp_f32_e32 v113, v113
	v_pk_mul_f32 v[28:29], v[28:29], v[148:149]
	v_pk_mul_f32 v[30:31], v[30:31], v[114:115]
	v_pk_mul_f32 v[20:21], v[20:21], v[126:127]
	v_pk_mul_f32 v[22:23], v[22:23], v[112:113]
	v_pk_mul_f32 v[24:25], v[24:25], v[28:29]
	v_pk_mul_f32 v[26:27], v[26:27], v[30:31]
	v_pk_mul_f32 v[16:17], v[16:17], v[20:21]
	v_pk_mul_f32 v[18:19], v[18:19], v[22:23]
	v_cvt_pk_bf16_f32 v19, v18, v19
	v_cvt_pk_bf16_f32 v18, v16, v17
	v_cvt_pk_bf16_f32 v16, v24, v25
	v_cvt_pk_bf16_f32 v17, v26, v27
	s_mov_b32 s100, 0xdc000
	v_lshl_add_u64 v[20:21], v[118:119], 0, s[100:101]
	global_store_dwordx4 v[20:21], v[16:19], off
	s_waitcnt lgkmcnt(0)
	v_pk_mul_f32 v[12:13], v[12:13], v[124:125] op_sel:[0,1] op_sel_hi:[1,1]
	v_pk_mul_f32 v[14:15], v[14:15], v[124:125] op_sel:[0,1] op_sel_hi:[1,1]
	v_pk_mul_f32 v[4:5], v[4:5], v[124:125] op_sel:[0,1] op_sel_hi:[1,1]
	v_pk_mul_f32 v[6:7], v[6:7], v[124:125] op_sel:[0,1] op_sel_hi:[1,1]
	v_pk_mul_f32 v[8:9], v[8:9], v[124:125] op_sel:[0,1] op_sel_hi:[1,1]
	v_pk_mul_f32 v[10:11], v[10:11], v[124:125] op_sel:[0,1] op_sel_hi:[1,1]
	v_pk_mul_f32 v[0:1], v[0:1], v[124:125] op_sel:[0,1] op_sel_hi:[1,1]
	v_pk_mul_f32 v[2:3], v[2:3], v[124:125] op_sel:[0,1] op_sel_hi:[1,1]
	v_pk_mul_f32 v[148:149], v[12:13], v[144:145] op_sel:[0,1] op_sel_hi:[1,1]
	v_pk_mul_f32 v[114:115], v[14:15], v[144:145] op_sel:[0,1] op_sel_hi:[1,1]
	v_pk_mul_f32 v[126:127], v[4:5], v[144:145] op_sel:[0,1] op_sel_hi:[1,1]
	v_pk_mul_f32 v[112:113], v[6:7], v[144:145] op_sel:[0,1] op_sel_hi:[1,1]
	v_exp_f32_e32 v148, v148
	v_exp_f32_e32 v149, v149
	v_exp_f32_e32 v114, v114
	v_exp_f32_e32 v115, v115
	v_exp_f32_e32 v126, v126
	v_exp_f32_e32 v127, v127
	v_exp_f32_e32 v112, v112
	v_exp_f32_e32 v113, v113
	v_pk_add_f32 v[148:149], v[148:149], v[116:117] op_sel_hi:[1,0]
	v_pk_add_f32 v[114:115], v[114:115], v[116:117] op_sel_hi:[1,0]
	v_pk_add_f32 v[126:127], v[126:127], v[116:117] op_sel_hi:[1,0]
	v_pk_add_f32 v[112:113], v[112:113], v[116:117] op_sel_hi:[1,0]
	v_rcp_f32_e32 v148, v148
	v_rcp_f32_e32 v149, v149
	v_rcp_f32_e32 v114, v114
	v_rcp_f32_e32 v115, v115
	v_rcp_f32_e32 v126, v126
	v_rcp_f32_e32 v127, v127
	v_rcp_f32_e32 v112, v112
	v_rcp_f32_e32 v113, v113
	v_pk_mul_f32 v[12:13], v[12:13], v[148:149]
	v_pk_mul_f32 v[14:15], v[14:15], v[114:115]
	v_pk_mul_f32 v[4:5], v[4:5], v[126:127]
	v_pk_mul_f32 v[6:7], v[6:7], v[112:113]
	v_pk_mul_f32 v[8:9], v[8:9], v[12:13]
	v_pk_mul_f32 v[10:11], v[10:11], v[14:15]
	v_pk_mul_f32 v[0:1], v[0:1], v[4:5]
	v_pk_mul_f32 v[2:3], v[2:3], v[6:7]
	v_cvt_pk_bf16_f32 v3, v2, v3
	v_cvt_pk_bf16_f32 v2, v0, v1
	v_cvt_pk_bf16_f32 v0, v8, v9
	v_cvt_pk_bf16_f32 v1, v10, v11
	s_mov_b32 s100, 0xf2000
	v_lshl_add_u64 v[4:5], v[118:119], 0, s[100:101]
	s_mov_b64 s[0:1], -1
	global_store_dwordx4 v[4:5], v[0:3], off
	s_cbranch_vccnz .LBB0_31
	s_andn2_b64 vcc, exec, s[8:9]
	s_cbranch_vccnz .LBB0_30
	s_barrier
	s_branch .LBB0_30
